# more kernarg pointer reloads via s_load (swa/lru/mlstm_local/mlstm_out/lru_out unit starts, P6/GEMM-2/P7 prologues), their VMEM waits dropped
# speedup vs baseline: 1.0234x; 1.0064x over previous
.LBB0_287:
	s_mov_b64 s[6:7], s[62:63]
	v_mov_b32_e32 v0, 0
	s_load_dwordx2 s[12:13], s[6:7], 0xc0
	s_load_dwordx2 s[14:15], s[6:7], 0x10
	s_load_dwordx2 s[16:17], s[6:7], 0x78
	s_bfe_u32 s76, s86, 0x40001
	v_mov_b32_e32 v8, v208
	s_and_b32 s5, s86, 1
	s_lshl_b32 s10, s76, 7
	s_lshl_b32 s9, s5, 6
	s_add_i32 s8, s10, 0xffffff80
	v_and_b32_e32 v9, 7, v8
	v_ashrrev_i32_e32 v1, 3, v8
	s_lshl_b32 s6, s86, 6
	v_lshl_or_b32 v5, v9, 3, s9
	v_add_u32_e32 v15, s8, v1
	s_mov_b64 s[2:3], 0x74c2800
	v_mov_b32_e32 v2, 0
	v_mov_b32_e32 v3, 0
	v_mov_b32_e32 v4, 0
	s_and_b32 s11, s6, 0xfffff800
	v_cmp_lt_i32_e32 vcc, -1, v15
	v_lshlrev_b32_e32 v14, 1, v5
	v_mov_b32_e32 v5, 0
	s_waitcnt lgkmcnt(0)
	v_mov_b32_e32 v6, s12
	v_mov_b32_e32 v7, s13
	v_mov_b32_e32 v12, s14
	v_mov_b32_e32 v13, s15
	v_mov_b32_e32 v10, s16
	v_mov_b32_e32 v11, s17
	v_lshl_add_u64 v[112:113], v[6:7], 0, s[2:3]
	s_mov_b32 s0, 0x200000
	s_mov_b64 s[2:3], 0x200000
	v_lshl_add_u32 v16, v9, 4, 0
	v_mov_b32_e32 v15, v167
	v_mov_b32_e32 v49, 0
	v_add_u32_e32 v44, 0, v1
	v_mad_u32_u24 v140, v44, s94, v16
	v_add_u32_e32 v45, s8, v44
	v_cmp_lt_i32_e32 vcc, -1, v45
	v_mov_b32_e32 v116, 0
	v_mov_b32_e32 v117, 0
	v_mov_b32_e32 v118, 0
	v_mov_b32_e32 v119, 0
	s_and_saveexec_b64 s[6:7], vcc
	s_cbranch_execz .Lswa_k0
	v_add_u32_e32 v46, s11, v45
	v_lshrrev_b32_e32 v47, 8, v46
	v_mad_u64_u32 v[132:133], s[12:13], v47, s77, v[112:113]
	v_lshlrev_b32_e32 v48, 9, v46
	v_and_b32_e32 v48, 0x1fe00, v48
	v_lshl_add_u64 v[132:133], v[132:133], 0, v[48:49]
	v_lshl_add_u64 v[132:133], v[132:133], 0, v[14:15]
	v_lshl_add_u64 v[132:133], v[132:133], 0, s[2:3]
	global_load_dwordx4 v[116:119], v[132:133], off

.LBB0_311:
	s_mov_b64 s[8:9], s[62:63]
	s_load_dwordx2 s[10:11], s[8:9], 0x70
	s_load_dwordx4 s[16:19], s[8:9], 0x60
	s_load_dwordx4 s[40:43], s[8:9], 0x50
	s_load_dwordx4 s[72:75], s[8:9], 0x40
	s_load_dwordx2 s[22:23], s[8:9], 0xc0
	v_mov_b32_e32 v66, v208
	v_mov_b32_e32 v37, v167
	v_ashrrev_i32_e32 v14, 6, v66
	v_ashrrev_i32_e32 v15, 31, v14
	v_lshlrev_b64 v[14:15], 12, v[14:15]
	v_lshl_add_u64 v[14:15], v[14:15], 0, s[6:7]
	v_and_b32_e32 v70, 15, v66
	v_lshlrev_b64 v[14:15], 2, v[14:15]
	v_bfe_u32 v67, v66, 4, 2
	v_mov_b32_e32 v39, v167
	v_mov_b32_e32 v53, v167
	v_mov_b32_e32 v43, v167
	v_mov_b32_e32 v47, v167
	v_mov_b32_e32 v69, v167
	v_mov_b32_e32 v79, v167
	v_mov_b32_e32 v95, v167
	v_mov_b32_e32 v87, v167
	v_mov_b32_e32 v91, v167
	v_and_b32_e32 v73, 0xffffffc0, v66
	s_mov_b64 s[8:9], 0x74c2800
	s_waitcnt lgkmcnt(0)
	v_mov_b32_e32 v12, s10
	v_mov_b32_e32 v13, s11
	v_mov_b32_e32 v4, s16
	v_mov_b32_e32 v5, s17
	v_mov_b32_e32 v6, s18
	v_mov_b32_e32 v7, s19
	v_mov_b32_e32 v8, s40
	v_mov_b32_e32 v9, s41
	v_mov_b32_e32 v10, s42
	v_mov_b32_e32 v11, s43
	v_mov_b32_e32 v0, s72
	v_mov_b32_e32 v1, s73
	v_mov_b32_e32 v2, s74
	v_mov_b32_e32 v3, s75
	v_mov_b32_e32 v64, s22
	v_mov_b32_e32 v65, s23
	v_lshl_add_u64 v[4:5], v[4:5], 0, v[14:15]
	s_waitcnt vmcnt(2)
	v_lshl_add_u64 v[8:9], v[8:9], 0, v[14:15]
	v_lshlrev_b32_e32 v14, 2, v70
	v_lshl_or_b32 v166, v67, 11, v14
	v_or_b32_e32 v36, 0x2000, v166
	v_or_b32_e32 v38, 0x2100, v166
	v_or_b32_e32 v52, 0x2700, v166
	v_lshl_add_u64 v[16:17], v[8:9], 0, v[166:167]
	v_lshl_add_u64 v[14:15], v[4:5], 0, v[166:167]
	v_lshl_add_u64 v[34:35], v[8:9], 0, v[36:37]
	v_lshl_add_u64 v[40:41], v[8:9], 0, v[38:39]
	v_lshl_add_u64 v[50:51], v[8:9], 0, v[52:53]
	global_load_dword v18, v[16:17], off
	global_load_dword v19, v[16:17], off offset:256
	global_load_dword v20, v[14:15], off
	global_load_dword v21, v[14:15], off offset:256
	global_load_dword v22, v[16:17], off offset:512
	global_load_dword v23, v[16:17], off offset:768
	global_load_dword v24, v[14:15], off offset:512
	global_load_dword v26, v[14:15], off offset:768
	global_load_dword v27, v[16:17], off offset:1024
	global_load_dword v29, v[16:17], off offset:1280
	global_load_dword v30, v[14:15], off offset:1024
	global_load_dword v31, v[14:15], off offset:1280
	global_load_dword v32, v[16:17], off offset:1536
	global_load_dword v33, v[16:17], off offset:1792
	global_load_dword v25, v[14:15], off offset:1536
	global_load_dword v28, v[14:15], off offset:1792
	v_lshl_add_u64 v[36:37], v[4:5], 0, v[36:37]
	global_load_dword v34, v[34:35], off
	v_lshl_add_u64 v[38:39], v[4:5], 0, v[38:39]
	global_load_dword v35, v[40:41], off
	global_load_dword v60, v[50:51], off
	v_or_b32_e32 v40, 0x2200, v166
	v_mov_b32_e32 v41, v167
	v_or_b32_e32 v42, 0x2300, v166
	global_load_dword v36, v[36:37], off
	v_lshl_add_u64 v[44:45], v[8:9], 0, v[42:43]
	global_load_dword v37, v[38:39], off
	v_lshl_add_u64 v[38:39], v[8:9], 0, v[40:41]
	global_load_dword v38, v[38:39], off
	v_lshl_add_u64 v[40:41], v[4:5], 0, v[40:41]
	global_load_dword v39, v[44:45], off
	v_lshl_add_u64 v[42:43], v[4:5], 0, v[42:43]
	v_or_b32_e32 v44, 0x2400, v166
	v_mov_b32_e32 v45, v167
	v_or_b32_e32 v46, 0x2500, v166
	global_load_dword v40, v[40:41], off
	v_lshl_add_u64 v[48:49], v[8:9], 0, v[46:47]
	global_load_dword v41, v[42:43], off
	v_lshl_add_u64 v[42:43], v[8:9], 0, v[44:45]
	global_load_dword v42, v[42:43], off
	v_lshl_add_u64 v[44:45], v[4:5], 0, v[44:45]
	global_load_dword v43, v[48:49], off
	v_lshl_add_u64 v[46:47], v[4:5], 0, v[46:47]
	v_or_b32_e32 v48, 0x2600, v166
	v_mov_b32_e32 v49, v167
	global_load_dword v44, v[44:45], off
	v_or_b32_e32 v68, 0x2040, v166
	global_load_dword v45, v[46:47], off
	v_lshl_add_u64 v[46:47], v[8:9], 0, v[48:49]
	v_lshl_add_u64 v[48:49], v[4:5], 0, v[48:49]
	v_or_b32_e32 v78, 0x2140, v166
	v_or_b32_e32 v94, 0x2740, v166
	global_load_dword v50, v[48:49], off
	v_lshl_add_u64 v[48:49], v[4:5], 0, v[52:53]
	v_lshl_add_u64 v[74:75], v[8:9], 0, v[68:69]
	v_lshl_add_u64 v[76:77], v[8:9], 0, v[78:79]
	v_lshl_add_u64 v[68:69], v[4:5], 0, v[68:69]
	v_lshl_add_u64 v[92:93], v[8:9], 0, v[94:95]
	global_load_dword v46, v[46:47], off
	s_nop 0
	global_load_dword v56, v[48:49], off
	global_load_dword v47, v[16:17], off offset:64
	s_nop 0
	global_load_dword v48, v[16:17], off offset:320
	global_load_dword v49, v[14:15], off offset:64
	global_load_dword v51, v[14:15], off offset:320
	global_load_dword v52, v[16:17], off offset:576
	global_load_dword v53, v[16:17], off offset:832
	global_load_dword v54, v[14:15], off offset:576
	global_load_dword v57, v[14:15], off offset:832
	global_load_dword v58, v[16:17], off offset:1088
	global_load_dword v61, v[16:17], off offset:1344
	global_load_dword v62, v[14:15], off offset:1088
	global_load_dword v63, v[14:15], off offset:1344
	global_load_dword v71, v[16:17], off offset:1600
	global_load_dword v72, v[16:17], off offset:1856
	global_load_dword v55, v[14:15], off offset:1600
	global_load_dword v59, v[14:15], off offset:1856
	v_or_b32_e32 v86, 0x2340, v166
	global_load_dword v74, v[74:75], off
	v_lshl_add_u64 v[84:85], v[8:9], 0, v[86:87]
	global_load_dword v92, v[92:93], off
	v_or_b32_e32 v90, 0x2540, v166
	global_load_dword v75, v[76:77], off
	v_lshl_add_u64 v[88:89], v[8:9], 0, v[90:91]
	global_load_dword v76, v[68:69], off
	v_lshl_add_u64 v[68:69], v[4:5], 0, v[78:79]
	global_load_dword v77, v[68:69], off
	v_or_b32_e32 v68, 0x2240, v166
	v_mov_b32_e32 v69, v167
	v_lshl_add_u64 v[78:79], v[8:9], 0, v[68:69]
	v_lshl_add_u64 v[68:69], v[4:5], 0, v[68:69]
	global_load_dword v78, v[78:79], off
	s_waitcnt vmcnt(54)
	v_lshl_add_u64 v[100:101], v[64:65], 0, s[8:9]
	global_load_dword v79, v[84:85], off
	s_mul_i32 s9, s83, 0xfffffa00
	global_load_dword v84, v[68:69], off
	v_lshl_add_u64 v[68:69], v[4:5], 0, v[86:87]
	global_load_dword v85, v[68:69], off
	v_or_b32_e32 v68, 0x2440, v166
	v_mov_b32_e32 v69, v167
	v_lshl_add_u64 v[86:87], v[8:9], 0, v[68:69]
	v_lshl_add_u64 v[68:69], v[4:5], 0, v[68:69]
	global_load_dword v86, v[86:87], off
	s_lshl_b32 s8, s15, 6
	global_load_dword v87, v[88:89], off
	s_nop 0
	global_load_dword v88, v[68:69], off
	v_lshl_add_u64 v[68:69], v[4:5], 0, v[90:91]
	global_load_dword v89, v[68:69], off
	v_or_b32_e32 v68, 0x2640, v166
	v_mov_b32_e32 v69, v167
	v_lshl_add_u64 v[90:91], v[8:9], 0, v[68:69]
	v_lshl_add_u64 v[68:69], v[4:5], 0, v[68:69]
	global_load_dword v90, v[90:91], off
	s_nop 0
	global_load_dword v91, v[68:69], off
	v_lshl_add_u64 v[68:69], v[4:5], 0, v[94:95]
	global_load_dword v105, v[68:69], off
	global_load_dword v93, v[16:17], off offset:128
	global_load_dword v94, v[16:17], off offset:384
	global_load_dword v95, v[14:15], off offset:128
	global_load_dword v96, v[14:15], off offset:384
	global_load_dword v97, v[16:17], off offset:640
	global_load_dword v98, v[16:17], off offset:896
	global_load_dword v99, v[14:15], off offset:640
	global_load_dword v106, v[14:15], off offset:896
	global_load_dword v107, v[16:17], off offset:1152
	global_load_dword v109, v[16:17], off offset:1408
	global_load_dword v110, v[14:15], off offset:1152
	global_load_dword v111, v[14:15], off offset:1408
	global_load_dword v112, v[16:17], off offset:1664
	global_load_dword v113, v[16:17], off offset:1920
	global_load_dword v104, v[14:15], off offset:1664
	global_load_dword v108, v[14:15], off offset:1920
	v_or_b32_e32 v68, 0x2080, v166
	v_mov_b32_e32 v69, v167
	v_lshl_add_u64 v[102:103], v[8:9], 0, v[68:69]
	global_load_dword v114, v[102:103], off
	v_or_b32_e32 v102, 0x2180, v166
	v_mov_b32_e32 v103, v167
	v_lshl_add_u64 v[116:117], v[8:9], 0, v[102:103]
	v_lshl_add_u64 v[68:69], v[4:5], 0, v[68:69]
	global_load_dword v116, v[116:117], off
	s_nop 0
	global_load_dword v117, v[68:69], off
	v_lshl_add_u64 v[68:69], v[4:5], 0, v[102:103]
	global_load_dword v118, v[68:69], off
	v_or_b32_e32 v68, 0x2280, v166
	v_mov_b32_e32 v69, v167
	v_lshl_add_u64 v[102:103], v[8:9], 0, v[68:69]
	global_load_dword v119, v[102:103], off
	v_or_b32_e32 v102, 0x2380, v166
	v_mov_b32_e32 v103, v167
	v_lshl_add_u64 v[120:121], v[8:9], 0, v[102:103]
	v_lshl_add_u64 v[68:69], v[4:5], 0, v[68:69]
	global_load_dword v120, v[120:121], off
	s_nop 0
	global_load_dword v121, v[68:69], off
	v_lshl_add_u64 v[68:69], v[4:5], 0, v[102:103]
	global_load_dword v122, v[68:69], off
	v_or_b32_e32 v68, 0x2480, v166
	v_mov_b32_e32 v69, v167
	v_lshl_add_u64 v[102:103], v[8:9], 0, v[68:69]
	global_load_dword v123, v[102:103], off
	v_or_b32_e32 v102, 0x2580, v166
	v_mov_b32_e32 v103, v167
	v_lshl_add_u64 v[124:125], v[8:9], 0, v[102:103]
	v_lshl_add_u64 v[68:69], v[4:5], 0, v[68:69]
	global_load_dword v124, v[124:125], off
	s_nop 0
	global_load_dword v125, v[68:69], off
	v_lshl_add_u64 v[68:69], v[4:5], 0, v[102:103]
	global_load_dword v140, v[68:69], off
	v_or_b32_e32 v68, 0x2680, v166
	v_mov_b32_e32 v69, v167
	v_lshl_add_u64 v[102:103], v[8:9], 0, v[68:69]
	global_load_dword v141, v[102:103], off
	v_or_b32_e32 v102, 0x2780, v166
	v_mov_b32_e32 v103, v167
	v_lshl_add_u64 v[68:69], v[4:5], 0, v[68:69]
	v_lshl_add_u64 v[126:127], v[8:9], 0, v[102:103]
	global_load_dword v142, v[68:69], off
	v_lshl_add_u64 v[68:69], v[4:5], 0, v[102:103]
	global_load_dword v143, v[126:127], off
	global_load_dword v145, v[68:69], off
	global_load_dword v144, v[16:17], off offset:192
	global_load_dword v146, v[16:17], off offset:448
	global_load_dword v147, v[14:15], off offset:192
	global_load_dword v149, v[14:15], off offset:448
	global_load_dword v150, v[16:17], off offset:704
	global_load_dword v151, v[16:17], off offset:960
	global_load_dword v152, v[14:15], off offset:704
	global_load_dword v153, v[14:15], off offset:960
	global_load_dword v154, v[16:17], off offset:1216
	global_load_dword v155, v[16:17], off offset:1472
	global_load_dword v156, v[14:15], off offset:1216
	global_load_dword v157, v[14:15], off offset:1472
	global_load_dword v158, v[16:17], off offset:1728
	global_load_dword v161, v[16:17], off offset:1984
	global_load_dword v160, v[14:15], off offset:1728
	global_load_dword v162, v[14:15], off offset:1984
	v_or_b32_e32 v14, 0x20c0, v166
	v_mov_b32_e32 v15, v167
	v_lshl_add_u64 v[16:17], v[8:9], 0, v[14:15]
	global_load_dword v163, v[16:17], off
	v_or_b32_e32 v16, 0x21c0, v166
	v_mov_b32_e32 v17, v167
	v_lshl_add_u64 v[14:15], v[4:5], 0, v[14:15]
	global_load_dword v165, v[14:15], off
	v_lshl_add_u64 v[14:15], v[4:5], 0, v[16:17]
	global_load_dword v169, v[14:15], off
	v_or_b32_e32 v14, 0x22c0, v166
	v_mov_b32_e32 v15, v167
	v_lshl_add_u64 v[68:69], v[8:9], 0, v[16:17]
	v_lshl_add_u64 v[16:17], v[8:9], 0, v[14:15]
	global_load_dword v164, v[68:69], off
	global_load_dword v176, v[16:17], off
	v_or_b32_e32 v16, 0x23c0, v166
	v_mov_b32_e32 v17, v167
	v_lshl_add_u64 v[14:15], v[4:5], 0, v[14:15]
	global_load_dword v178, v[14:15], off
	v_lshl_add_u64 v[14:15], v[4:5], 0, v[16:17]
	global_load_dword v180, v[14:15], off
	v_or_b32_e32 v14, 0x24c0, v166
	v_mov_b32_e32 v15, v167
	v_lshl_add_u64 v[68:69], v[8:9], 0, v[16:17]
	v_lshl_add_u64 v[16:17], v[8:9], 0, v[14:15]
	global_load_dword v177, v[68:69], off
	global_load_dword v182, v[16:17], off
	v_or_b32_e32 v16, 0x25c0, v166
	v_mov_b32_e32 v17, v167
	v_lshl_add_u64 v[14:15], v[4:5], 0, v[14:15]
	global_load_dword v179, v[14:15], off
	v_lshl_add_u64 v[14:15], v[4:5], 0, v[16:17]
	global_load_dword v181, v[14:15], off
	v_or_b32_e32 v14, 0x26c0, v166
	v_mov_b32_e32 v15, v167
	v_or_b32_e32 v166, 0x27c0, v166
	v_lshl_add_u64 v[68:69], v[8:9], 0, v[16:17]
	v_lshl_add_u64 v[16:17], v[8:9], 0, v[14:15]
	v_lshl_add_u64 v[8:9], v[8:9], 0, v[166:167]
	global_load_dword v184, v[68:69], off
	global_load_dword v183, v[16:17], off
	global_load_dword v185, v[8:9], off
	v_lshl_add_u64 v[8:9], v[4:5], 0, v[14:15]
	v_lshl_add_u64 v[4:5], v[4:5], 0, v[166:167]
	global_load_dword v186, v[8:9], off
	global_load_dword v187, v[4:5], off
	v_add_u32_e32 v4, s37, v73
	v_or_b32_e32 v4, v4, v70
	v_ashrrev_i32_e32 v5, 31, v4
	v_lshlrev_b64 v[4:5], 2, v[4:5]
	v_lshl_add_u64 v[8:9], v[10:11], 0, v[4:5]
	v_lshl_add_u64 v[6:7], v[6:7], 0, v[4:5]
	v_lshl_add_u64 v[4:5], v[12:13], 0, v[4:5]
	global_load_dword v126, v[8:9], off
	global_load_dword v127, v[6:7], off
	global_load_dword v188, v[4:5], off
	global_load_dword v128, v[8:9], off offset:64
	global_load_dword v129, v[6:7], off offset:64
	global_load_dword v159, v[4:5], off offset:64
	global_load_dword v130, v[8:9], off offset:128
	global_load_dword v131, v[6:7], off offset:128
	global_load_dword v148, v[4:5], off offset:128
	global_load_dword v132, v[8:9], off offset:192
	global_load_dword v133, v[6:7], off offset:192
	global_load_dword v115, v[4:5], off offset:192
	v_add_u32_e32 v4, s5, v66
	v_ashrrev_i32_e32 v5, 31, v4
	v_lshl_add_u64 v[6:7], v[4:5], 2, v[0:1]
	global_load_dword v134, v[6:7], off
	global_load_dword v135, v[6:7], off offset:2048
	v_add_u32_e32 v6, s12, v66
	v_ashrrev_i32_e32 v7, 31, v6
	v_lshl_add_u64 v[6:7], v[6:7], 2, v[0:1]
	global_load_dword v136, v[6:7], off
	v_add_u32_e32 v6, s13, v66
	v_ashrrev_i32_e32 v7, 31, v6
	v_lshl_add_u64 v[0:1], v[6:7], 2, v[0:1]
	global_load_dword v137, v[0:1], off
	v_add_u32_e32 v0, s9, v4
	v_ashrrev_i32_e32 v1, 31, v0
	v_lshl_add_u64 v[0:1], v[0:1], 2, v[2:3]
	global_load_dword v138, v[0:1], off
	s_and_b32 s9, s15, 31
	v_add_u32_e32 v0, 0xa00, v66
	s_cmp_lg_u32 s9, 0
	v_and_b32_e32 v166, 0xff, v66
	v_ashrrev_i32_e32 v102, 8, v0
	s_cbranch_scc0 .LBB0_321
	s_add_i32 s10, s8, -3
	s_ashr_i32 s11, s10, 31
	s_lshr_b64 s[16:17], s[10:11], 8
	v_ashrrev_i32_e32 v103, 31, v102
	v_mad_u64_u32 v[0:1], s[16:17], s16, 49, v[102:103]
	v_mov_b32_e32 v2, v1
	s_lshr_b32 s9, s11, 8
	v_mad_u64_u32 v[2:3], s[16:17], s9, 49, v[2:3]
	v_mov_b32_e32 v1, v2
	v_lshlrev_b64 v[0:1], 17, v[0:1]
	s_lshl_b32 s9, s10, 9
	v_lshl_add_u64 v[0:1], v[100:101], 0, v[0:1]
	s_and_b32 s96, s9, 0x1fa00
	v_lshl_add_u64 v[0:1], v[0:1], 0, s[96:97]
	v_lshlrev_b32_e32 v2, 1, v166
	v_mov_b32_e32 v3, v167
	v_lshl_add_u64 v[0:1], v[0:1], 0, v[2:3]
	global_load_ushort v139, v[0:1], off
	s_add_i32 s10, s8, -2
	s_ashr_i32 s11, s10, 31
	s_lshr_b64 s[16:17], s[10:11], 8
	s_lshr_b32 s9, s11, 8
	v_mad_u64_u32 v[0:1], s[16:17], s16, 49, v[102:103]
	v_mov_b32_e32 v4, v1
	v_mad_u64_u32 v[4:5], s[16:17], s9, 49, v[4:5]
	s_lshl_b32 s9, s10, 9
	s_add_i32 s10, s8, -1
	s_ashr_i32 s11, s10, 31
	s_lshr_b64 s[16:17], s[10:11], 8
	v_mov_b32_e32 v1, v4
	v_mad_u64_u32 v[4:5], s[16:17], s16, 49, v[102:103]
	s_and_b32 s96, s9, 0x1fc00
	v_mov_b32_e32 v6, v5
	s_lshr_b32 s9, s11, 8
	v_mad_u64_u32 v[6:7], s[16:17], s9, 49, v[6:7]
	v_lshlrev_b64 v[0:1], 17, v[0:1]
	v_mov_b32_e32 v5, v6
	v_lshl_add_u64 v[0:1], v[100:101], 0, v[0:1]
	v_lshlrev_b64 v[4:5], 17, v[4:5]
	s_lshl_b32 s9, s10, 9
	v_lshl_add_u64 v[0:1], v[0:1], 0, s[96:97]
	v_lshl_add_u64 v[4:5], v[100:101], 0, v[4:5]
	s_and_b32 s96, s9, 0x1fe00
	v_lshl_add_u64 v[4:5], v[4:5], 0, s[96:97]
	v_lshl_add_u64 v[0:1], v[0:1], 0, v[2:3]
	v_lshl_add_u64 v[2:3], v[4:5], 0, v[2:3]
	global_load_ushort v68, v[2:3], off
	s_nop 0
	global_load_ushort v69, v[0:1], off
	s_cbranch_execnz .LBB0_314

.LBB0_853:
	s_mov_b64 s[10:11], s[62:63]
	s_load_dwordx4 s[40:43], s[10:11], 0x28
	s_load_dwordx2 s[2:3], s[10:11], 0xc0
	v_mov_b32_e32 v34, v208
	s_bfe_u32 s12, s23, 0x20004
	s_lshl_b32 s10, s12, 7
	v_and_b32_e32 v35, 63, v34
	v_lshl_or_b32 v7, v35, 1, s10
	v_lshlrev_b32_e32 v166, 2, v7
	v_ashrrev_i32_e32 v28, 6, v34
	s_and_b32 s13, s5, 0x780
	v_lshlrev_b32_e32 v16, 4, v28
	v_or_b32_e32 v17, 0x200, v7
	v_add_u32_e32 v6, s13, v16
	s_waitcnt lgkmcnt(0)
	v_mov_b32_e32 v0, s40
	v_mov_b32_e32 v1, s41
	v_mov_b32_e32 v2, s42
	v_mov_b32_e32 v3, s43
	v_mov_b32_e32 v32, s2
	v_mov_b32_e32 v33, s3
	v_lshl_add_u64 v[0:1], v[0:1], 0, s[14:15]
	v_lshl_add_u64 v[4:5], v[0:1], 0, v[166:167]
	v_readfirstlane_b32 s10, v0
	v_add_co_u32_e32 v0, vcc, 0x1000, v4
	v_readfirstlane_b32 s11, v1
	s_nop 0
	v_addc_co_u32_e32 v1, vcc, 0, v5, vcc
	global_load_dwordx2 v[10:11], v[0:1], off offset:2048
	v_add_co_u32_e32 v0, vcc, 0x2000, v4
	s_nop 0
	global_load_dwordx2 v[8:9], v166, s[10:11] offset:2048
	v_addc_co_u32_e32 v1, vcc, 0, v5, vcc
	global_load_dwordx2 v[12:13], v[0:1], off offset:2048
	v_add_co_u32_e32 v0, vcc, 0x3000, v4
	v_lshrrev_b32_e32 v166, 8, v17
	s_nop 0
	v_addc_co_u32_e32 v1, vcc, 0, v5, vcc
	global_load_dwordx2 v[14:15], v[0:1], off offset:2048
	v_cmp_gt_i32_e32 vcc, 3, v6
	v_and_b32_e32 v4, 0xfe, v7
	s_and_saveexec_b64 s[10:11], vcc
	s_xor_b64 s[10:11], exec, s[10:11]
	v_mov_b32_e32 v5, v167
	s_or_saveexec_b64 s[10:11], s[10:11]
	s_and_b32 s18, s22, 0xfffff800
	s_mov_b64 s[2:3], 0x74c2800
	v_add_u32_e32 v6, s18, v6
	s_waitcnt vmcnt(4)
	v_lshl_add_u64 v[0:1], v[32:33], 0, s[2:3]
	v_ashrrev_i32_e32 v7, 31, v6
	v_mov_b32_e32 v24, 0
	v_mov_b32_e32 v17, 0
	v_mov_b32_e32 v19, 0
	v_mov_b32_e32 v20, 0
	s_xor_b64 exec, exec, s[10:11]
	s_cbranch_execz .LBB0_857
	v_lshl_add_u64 v[18:19], v[6:7], 0, -3
	v_alignbit_b32 v5, v19, v18, 8
	v_mad_u64_u32 v[20:21], s[20:21], v5, 49, v[166:167]
	v_mad_u32_u24 v21, v19, 49, v21
	v_lshlrev_b64 v[20:21], 17, v[20:21]
	v_lshlrev_b32_e32 v5, 9, v18
	v_lshl_add_u64 v[20:21], v[0:1], 0, v[20:21]
	v_and_b32_e32 v18, 0x1fe00, v5
	v_mov_b32_e32 v19, v167
	v_lshl_add_u64 v[18:19], v[20:21], 0, v[18:19]
	v_lshlrev_b32_e32 v20, 1, v4
	v_mov_b32_e32 v21, v167
	v_lshl_add_u64 v[18:19], v[18:19], 0, v[20:21]
	global_load_dword v17, v[18:19], off
	v_lshl_add_u64 v[18:19], v[6:7], 0, -2
	v_alignbit_b32 v5, v19, v18, 8
	v_mad_u64_u32 v[22:23], s[20:21], v5, 49, v[166:167]
	v_mad_u32_u24 v23, v19, 49, v23
	v_lshlrev_b64 v[22:23], 17, v[22:23]
	v_lshlrev_b32_e32 v5, 9, v18
	v_lshl_add_u64 v[22:23], v[0:1], 0, v[22:23]
	v_and_b32_e32 v18, 0x1fe00, v5
	v_mov_b32_e32 v19, v167
	v_lshl_add_u64 v[18:19], v[22:23], 0, v[18:19]
	v_lshl_add_u64 v[22:23], v[6:7], 0, -1
	v_alignbit_b32 v5, v23, v22, 8
	v_mad_u64_u32 v[26:27], s[20:21], v5, 49, v[166:167]
	v_mad_u32_u24 v27, v23, 49, v27
	v_lshlrev_b64 v[26:27], 17, v[26:27]
	v_lshlrev_b32_e32 v5, 9, v22
	v_lshl_add_u64 v[26:27], v[0:1], 0, v[26:27]
	v_and_b32_e32 v22, 0x1fe00, v5
	v_mov_b32_e32 v23, v167
	v_lshl_add_u64 v[22:23], v[26:27], 0, v[22:23]
	v_lshl_add_u64 v[18:19], v[18:19], 0, v[20:21]
	v_lshl_add_u64 v[20:21], v[22:23], 0, v[20:21]
	global_load_dword v19, v[18:19], off
	v_mov_b32_e32 v5, v167
	global_load_dword v20, v[20:21], off

.LBB0_1153:
	s_mov_b64 s[10:11], s[62:63]
	s_load_dwordx2 s[24:25], s[10:11], 0xc0
	s_load_dwordx2 s[30:31], s[10:11], 0x38
	s_load_dwordx2 s[34:35], s[10:11], 0x28
	s_load_dwordx2 s[42:43], s[10:11], 0x30
	v_mov_b32_e32 v64, v208
	s_and_b32 s13, s27, 0xfffff800
	s_and_b32 s6, s26, 0x780
	s_lshr_b32 s7, s28, 4
	v_ashrrev_i32_e32 v159, 6, v64
	s_bfe_u32 s12, s28, 0x20004
	s_or_b32 s5, s13, s6
	v_lshlrev_b32_e32 v95, 4, v159
	s_lshl_b32 s29, s12, 7
	s_bfe_u32 s96, s7, 0x10001
	v_and_b32_e32 v50, 63, v64
	v_add_u32_e32 v72, s5, v95
	s_or_b32 s7, s96, 6
	v_mov_b32_e32 v6, s29
	v_lshlrev_b32_e32 v160, 1, v50
	s_movk_i32 s0, 0xfe
	v_ashrrev_i32_e32 v73, 31, v72
	s_or_b32 s10, s96, 8
	v_mov_b32_e32 v166, s7
	v_bitop3_b32 v8, v160, s0, v6 bitop3:0xc8
	v_lshlrev_b32_e32 v6, 8, v72
	v_alignbit_b32 v52, v73, v72, 8
	v_mov_b32_e32 v5, v167
	v_mov_b32_e32 v4, s10
	v_and_b32_e32 v9, 0xf000, v6
	v_mad_u64_u32 v[6:7], s[10:11], v52, 49, v[166:167]
	v_mad_u64_u32 v[4:5], s[10:11], v52, 49, v[4:5]
	v_mad_u32_u24 v7, v73, 49, v7
	s_mov_b64 s[2:3], 0x74c2800
	v_mad_u32_u24 v5, v73, 49, v5
	v_lshlrev_b64 v[6:7], 17, v[6:7]
	v_lshlrev_b32_e32 v166, 1, v8
	v_lshlrev_b64 v[4:5], 17, v[4:5]
	v_mov_b32_e32 v19, v167
	v_lshlrev_b32_e32 v18, 1, v9
	v_lshlrev_b32_e32 v51, 3, v64
	v_or_b32_e32 v48, s29, v160
	s_lshl_b64 s[10:11], s[18:19], 2
	v_mov_b64_e32 v[30:31], s[96:97]
	s_waitcnt lgkmcnt(0)
	v_mov_b32_e32 v74, s24
	v_mov_b32_e32 v75, s25
	v_mov_b32_e32 v76, s30
	v_mov_b32_e32 v77, s31
	v_mov_b32_e32 v0, s34
	v_mov_b32_e32 v1, s35
	v_mov_b32_e32 v2, s42
	v_mov_b32_e32 v3, s43
	v_lshl_add_u64 v[20:21], v[74:75], 0, s[2:3]
	v_lshl_add_u64 v[6:7], v[20:21], 0, v[6:7]
	v_lshl_add_u64 v[4:5], v[20:21], 0, v[4:5]
	v_lshl_add_u64 v[6:7], v[6:7], 0, v[166:167]
	v_lshl_add_u64 v[4:5], v[4:5], 0, v[166:167]
	v_lshl_add_u64 v[6:7], v[6:7], 0, v[18:19]
	v_lshl_add_u64 v[4:5], v[4:5], 0, v[18:19]
	global_load_dword v158, v[6:7], off
	global_load_dword v156, v[6:7], off offset:512
	global_load_dword v154, v[6:7], off offset:1024
	global_load_dword v151, v[6:7], off offset:1536
	global_load_dword v149, v[6:7], off offset:2048
	global_load_dword v147, v[6:7], off offset:2560
	global_load_dword v145, v[6:7], off offset:3072
	global_load_dword v143, v[6:7], off offset:3584
	global_load_dword v157, v[4:5], off
	global_load_dword v155, v[4:5], off offset:512
	global_load_dword v153, v[4:5], off offset:1024
	global_load_dword v152, v[4:5], off offset:1536
	global_load_dword v150, v[4:5], off offset:2048
	global_load_dword v148, v[4:5], off offset:2560
	global_load_dword v146, v[4:5], off offset:3072
	global_load_dword v144, v[4:5], off offset:3584
	v_add_co_u32_e32 v6, vcc, s91, v6
	s_mov_b64 s[2:3], 0x800
	s_nop 0
	v_addc_co_u32_e32 v7, vcc, 0, v7, vcc
	v_add_co_u32_e32 v4, vcc, s91, v4
	v_add_u32_e32 v19, s6, v95
	s_nop 0
	v_addc_co_u32_e32 v5, vcc, 0, v5, vcc
	global_load_dword v141, v[6:7], off
	global_load_dword v139, v[6:7], off offset:512
	global_load_dword v137, v[6:7], off offset:1024
	global_load_dword v135, v[6:7], off offset:1536
	global_load_dword v133, v[6:7], off offset:2048
	global_load_dword v131, v[6:7], off offset:2560
	global_load_dword v129, v[6:7], off offset:3072
	global_load_dword v128, v[6:7], off offset:3584
	global_load_dword v142, v[4:5], off
	global_load_dword v140, v[4:5], off offset:512
	global_load_dword v138, v[4:5], off offset:1024
	global_load_dword v136, v[4:5], off offset:1536
	global_load_dword v134, v[4:5], off offset:2048
	global_load_dword v132, v[4:5], off offset:2560
	global_load_dword v130, v[4:5], off offset:3072
	global_load_dword v79, v[4:5], off offset:3584
	v_and_b32_e32 v4, 0xffffff80, v51
	v_ashrrev_i32_e32 v5, 31, v4
	v_lshlrev_b32_e32 v6, 4, v64
	v_add_u32_e32 v8, 0x1000, v4
	v_and_b32_e32 v10, 0xf0, v6
	v_lshlrev_b64 v[6:7], 1, v[4:5]
	v_ashrrev_i32_e32 v9, 31, v8
	v_or_b32_e32 v6, v6, v10
	v_lshlrev_b64 v[8:9], 1, v[8:9]
	v_lshl_add_u64 v[6:7], v[74:75], 0, v[6:7]
	v_or_b32_e32 v8, v8, v10
	v_lshl_add_u64 v[6:7], v[6:7], 0, s[14:15]
	v_lshl_add_u64 v[8:9], v[74:75], 0, v[8:9]
	v_lshl_add_u64 v[8:9], v[8:9], 0, s[14:15]
	global_load_dwordx4 v[36:39], v[6:7], off
	global_load_dwordx4 v[32:35], v[8:9], off
	v_add_u32_e32 v6, 0x2000, v4
	v_add_u32_e32 v4, 0x3000, v4
	v_ashrrev_i32_e32 v7, 31, v6
	v_ashrrev_i32_e32 v5, 31, v4
	v_lshlrev_b64 v[6:7], 1, v[6:7]
	v_lshlrev_b64 v[4:5], 1, v[4:5]
	v_or_b32_e32 v6, v6, v10
	v_or_b32_e32 v4, v4, v10
	v_lshl_add_u64 v[6:7], v[74:75], 0, v[6:7]
	v_lshl_add_u64 v[4:5], v[74:75], 0, v[4:5]
	v_lshl_add_u64 v[6:7], v[6:7], 0, s[14:15]
	v_lshl_add_u64 v[4:5], v[4:5], 0, s[14:15]
	global_load_dwordx4 v[44:47], v[6:7], off
	global_load_dwordx4 v[40:43], v[4:5], off
	v_lshlrev_b32_e32 v4, 2, v48
	v_mov_b32_e32 v5, v167
	s_waitcnt vmcnt(36)
	v_lshl_add_u64 v[0:1], v[0:1], 0, v[4:5]
	v_lshl_add_u64 v[4:5], v[0:1], 0, s[2:3]
	v_lshl_add_u64 v[8:9], v[0:1], 0, s[10:11]
	v_lshl_add_u64 v[14:15], v[4:5], 0, s[10:11]
	s_lshl_b64 s[10:11], s[20:21], 2
	v_lshl_add_u64 v[16:17], v[0:1], 0, s[10:11]
	v_lshl_add_u64 v[22:23], v[4:5], 0, s[10:11]
	s_lshl_b64 s[10:11], s[22:23], 2
	v_lshl_add_u64 v[6:7], s[16:17], 2, v[0:1]
	v_lshl_add_u64 v[4:5], v[4:5], 0, s[10:11]
	v_lshl_add_u64 v[24:25], v[0:1], 0, s[10:11]
	global_load_dwordx2 v[10:11], v[6:7], off
	global_load_dwordx2 v[12:13], v[8:9], off
	global_load_dwordx2 v[0:1], v[14:15], off
	s_nop 0
	global_load_dwordx2 v[6:7], v[6:7], off offset:2048
	s_nop 0
	global_load_dwordx2 v[16:17], v[16:17], off
	s_nop 0
	global_load_dwordx2 v[14:15], v[24:25], off
	s_nop 0
	global_load_dwordx2 v[4:5], v[4:5], off
	s_nop 0
	global_load_dwordx2 v[8:9], v[22:23], off
	v_cmp_gt_i32_e64 s[10:11], 3, v19
	s_and_saveexec_b64 s[6:7], s[10:11]
	s_xor_b64 s[6:7], exec, s[6:7]
	v_mov_b64_e32 v[30:31], s[96:97]
	s_or_saveexec_b64 s[6:7], s[6:7]
	v_add_u32_e32 v22, s13, v19
	v_ashrrev_i32_e32 v23, 31, v22
	v_lshl_add_u64 v[28:29], v[22:23], 0, -3
	v_lshl_add_u64 v[26:27], v[22:23], 0, -2
	v_lshl_add_u64 v[24:25], v[22:23], 0, -1
	v_mov_b32_e32 v100, 0
	v_alignbit_b32 v55, v29, v28, 8
	v_lshlrev_b32_e32 v54, 9, v28
	v_alignbit_b32 v53, v27, v26, 8
	v_lshlrev_b32_e32 v28, 9, v26
	v_alignbit_b32 v26, v25, v24, 8
	v_lshlrev_b32_e32 v19, 9, v24
	v_mov_b32_e32 v102, 0
	v_mov_b32_e32 v103, 0
	s_xor_b64 exec, exec, s[6:7]
	s_cbranch_execz .LBB0_1157
	v_mad_u64_u32 v[56:57], s[24:25], v55, 49, s[96:97]
	v_mad_u32_u24 v57, v29, 49, v57
	v_lshlrev_b64 v[56:57], 17, v[56:57]
	v_lshl_add_u64 v[56:57], v[20:21], 0, v[56:57]
	v_and_b32_e32 v58, 0x1fe00, v54
	v_mov_b32_e32 v59, v167
	v_lshl_add_u64 v[56:57], v[56:57], 0, v[58:59]
	v_lshl_add_u64 v[56:57], v[56:57], 0, v[166:167]
	global_load_dword v100, v[56:57], off
	v_mad_u64_u32 v[56:57], s[24:25], v53, 49, s[96:97]
	v_mad_u32_u24 v57, v27, 49, v57
	v_lshlrev_b64 v[56:57], 17, v[56:57]
	v_lshl_add_u64 v[56:57], v[20:21], 0, v[56:57]
	v_and_b32_e32 v58, 0x1fe00, v28
	v_lshl_add_u64 v[56:57], v[56:57], 0, v[58:59]
	v_lshl_add_u64 v[56:57], v[56:57], 0, v[166:167]
	global_load_dword v102, v[56:57], off
	v_mad_u64_u32 v[56:57], s[24:25], v26, 49, s[96:97]
	v_mad_u32_u24 v57, v25, 49, v57
	v_lshlrev_b64 v[56:57], 17, v[56:57]
	v_lshl_add_u64 v[56:57], v[20:21], 0, v[56:57]
	v_and_b32_e32 v58, 0x1fe00, v19
	v_lshl_add_u64 v[56:57], v[56:57], 0, v[58:59]
	v_lshl_add_u64 v[56:57], v[56:57], 0, v[166:167]
	global_load_dword v103, v[56:57], off

.LBB0_1307:
	s_mov_b64 s[8:9], s[62:63]
	s_load_dwordx2 s[14:15], s[8:9], 0xc0
	s_load_dwordx2 s[28:29], s[8:9], 0x38
	s_load_dwordx2 s[30:31], s[8:9], 0x28
	s_load_dwordx2 s[34:35], s[8:9], 0x30
	v_mov_b32_e32 v64, v208
	s_and_b32 s11, s25, 0xfffff800
	s_and_b32 s6, s24, 0x780
	s_lshr_b32 s7, s26, 4
	v_ashrrev_i32_e32 v202, 6, v64
	s_bfe_u32 s10, s26, 0x20004
	s_or_b32 s5, s11, s6
	v_lshlrev_b32_e32 v97, 4, v202
	s_lshl_b32 s27, s10, 7
	s_bfe_u32 s96, s7, 0x10001
	v_and_b32_e32 v50, 63, v64
	v_add_u32_e32 v74, s5, v97
	s_or_b32 s7, s96, 6
	v_mov_b32_e32 v6, s27
	v_lshlrev_b32_e32 v203, 1, v50
	s_movk_i32 s0, 0xfe
	v_ashrrev_i32_e32 v75, 31, v74
	s_or_b32 s8, s96, 8
	v_mov_b32_e32 v166, s7
	v_bitop3_b32 v8, v203, s0, v6 bitop3:0xc8
	v_lshlrev_b32_e32 v6, 8, v74
	v_alignbit_b32 v52, v75, v74, 8
	v_mov_b32_e32 v5, v167
	v_mov_b32_e32 v4, s8
	v_and_b32_e32 v9, 0xf000, v6
	v_mad_u64_u32 v[6:7], s[8:9], v52, 49, v[166:167]
	v_mad_u64_u32 v[4:5], s[8:9], v52, 49, v[4:5]
	v_mad_u32_u24 v7, v75, 49, v7
	s_mov_b64 s[2:3], 0x74c2800
	v_mad_u32_u24 v5, v75, 49, v5
	v_lshlrev_b64 v[6:7], 17, v[6:7]
	v_lshlrev_b32_e32 v166, 1, v8
	v_lshlrev_b64 v[4:5], 17, v[4:5]
	v_mov_b32_e32 v19, v167
	v_lshlrev_b32_e32 v18, 1, v9
	v_lshlrev_b32_e32 v51, 3, v64
	v_or_b32_e32 v204, s27, v203
	s_lshl_b64 s[8:9], s[18:19], 2
	v_mov_b64_e32 v[30:31], s[96:97]
	s_waitcnt lgkmcnt(0)
	v_mov_b32_e32 v76, s14
	v_mov_b32_e32 v77, s15
	v_mov_b32_e32 v78, s28
	v_mov_b32_e32 v79, s29
	v_mov_b32_e32 v0, s30
	v_mov_b32_e32 v1, s31
	v_mov_b32_e32 v2, s34
	v_mov_b32_e32 v3, s35
	v_lshl_add_u64 v[20:21], v[76:77], 0, s[2:3]
	v_lshl_add_u64 v[6:7], v[20:21], 0, v[6:7]
	v_lshl_add_u64 v[4:5], v[20:21], 0, v[4:5]
	v_lshl_add_u64 v[6:7], v[6:7], 0, v[166:167]
	v_lshl_add_u64 v[4:5], v[4:5], 0, v[166:167]
	v_lshl_add_u64 v[6:7], v[6:7], 0, v[18:19]
	v_lshl_add_u64 v[4:5], v[4:5], 0, v[18:19]
	global_load_dword v201, v[6:7], off
	global_load_dword v199, v[6:7], off offset:512
	global_load_dword v197, v[6:7], off offset:1024
	global_load_dword v194, v[6:7], off offset:1536
	global_load_dword v192, v[6:7], off offset:2048
	global_load_dword v190, v[6:7], off offset:2560
	global_load_dword v188, v[6:7], off offset:3072
	global_load_dword v186, v[6:7], off offset:3584
	global_load_dword v200, v[4:5], off
	global_load_dword v198, v[4:5], off offset:512
	global_load_dword v196, v[4:5], off offset:1024
	global_load_dword v195, v[4:5], off offset:1536
	global_load_dword v193, v[4:5], off offset:2048
	global_load_dword v191, v[4:5], off offset:2560
	global_load_dword v189, v[4:5], off offset:3072
	global_load_dword v187, v[4:5], off offset:3584
	v_add_co_u32_e32 v6, vcc, s91, v6
	s_mov_b64 s[2:3], 0x800
	s_nop 0
	v_addc_co_u32_e32 v7, vcc, 0, v7, vcc
	v_add_co_u32_e32 v4, vcc, s91, v4
	v_add_u32_e32 v19, s6, v97
	s_nop 0
	v_addc_co_u32_e32 v5, vcc, 0, v5, vcc
	global_load_dword v184, v[6:7], off
	global_load_dword v182, v[6:7], off offset:512
	global_load_dword v180, v[6:7], off offset:1024
	global_load_dword v178, v[6:7], off offset:1536
	global_load_dword v176, v[6:7], off offset:2048
	global_load_dword v165, v[6:7], off offset:2560
	global_load_dword v163, v[6:7], off offset:3072
	global_load_dword v162, v[6:7], off offset:3584
	global_load_dword v185, v[4:5], off
	global_load_dword v183, v[4:5], off offset:512
	global_load_dword v181, v[4:5], off offset:1024
	global_load_dword v179, v[4:5], off offset:1536
	global_load_dword v177, v[4:5], off offset:2048
	global_load_dword v169, v[4:5], off offset:2560
	global_load_dword v164, v[4:5], off offset:3072
	global_load_dword v161, v[4:5], off offset:3584
	v_and_b32_e32 v4, 0xffffff80, v51
	v_ashrrev_i32_e32 v5, 31, v4
	v_lshlrev_b32_e32 v6, 4, v64
	v_add_u32_e32 v8, 0x1000, v4
	v_and_b32_e32 v10, 0xf0, v6
	v_lshlrev_b64 v[6:7], 1, v[4:5]
	v_ashrrev_i32_e32 v9, 31, v8
	v_or_b32_e32 v6, v6, v10
	v_lshlrev_b64 v[8:9], 1, v[8:9]
	v_lshl_add_u64 v[6:7], v[76:77], 0, v[6:7]
	v_or_b32_e32 v8, v8, v10
	v_lshl_add_u64 v[6:7], v[6:7], 0, s[12:13]
	v_lshl_add_u64 v[8:9], v[76:77], 0, v[8:9]
	v_lshl_add_u64 v[8:9], v[8:9], 0, s[12:13]
	global_load_dwordx4 v[36:39], v[6:7], off
	global_load_dwordx4 v[32:35], v[8:9], off
	v_add_u32_e32 v6, 0x2000, v4
	v_add_u32_e32 v4, 0x3000, v4
	v_ashrrev_i32_e32 v7, 31, v6
	v_ashrrev_i32_e32 v5, 31, v4
	v_lshlrev_b64 v[6:7], 1, v[6:7]
	v_lshlrev_b64 v[4:5], 1, v[4:5]
	v_or_b32_e32 v6, v6, v10
	v_or_b32_e32 v4, v4, v10
	v_lshl_add_u64 v[6:7], v[76:77], 0, v[6:7]
	v_lshl_add_u64 v[4:5], v[76:77], 0, v[4:5]
	v_lshl_add_u64 v[6:7], v[6:7], 0, s[12:13]
	v_lshl_add_u64 v[4:5], v[4:5], 0, s[12:13]
	global_load_dwordx4 v[44:47], v[6:7], off
	global_load_dwordx4 v[40:43], v[4:5], off
	v_lshlrev_b32_e32 v4, 2, v204
	v_mov_b32_e32 v5, v167
	s_waitcnt vmcnt(36)
	v_lshl_add_u64 v[0:1], v[0:1], 0, v[4:5]
	v_lshl_add_u64 v[4:5], v[0:1], 0, s[2:3]
	v_lshl_add_u64 v[8:9], v[0:1], 0, s[8:9]
	v_lshl_add_u64 v[14:15], v[4:5], 0, s[8:9]
	s_lshl_b64 s[8:9], s[20:21], 2
	v_lshl_add_u64 v[16:17], v[0:1], 0, s[8:9]
	v_lshl_add_u64 v[22:23], v[4:5], 0, s[8:9]
	s_lshl_b64 s[8:9], s[22:23], 2
	v_lshl_add_u64 v[6:7], s[16:17], 2, v[0:1]
	v_lshl_add_u64 v[4:5], v[4:5], 0, s[8:9]
	v_lshl_add_u64 v[24:25], v[0:1], 0, s[8:9]
	global_load_dwordx2 v[10:11], v[6:7], off
	global_load_dwordx2 v[12:13], v[8:9], off
	global_load_dwordx2 v[0:1], v[14:15], off
	s_nop 0
	global_load_dwordx2 v[6:7], v[6:7], off offset:2048
	s_nop 0
	global_load_dwordx2 v[16:17], v[16:17], off
	s_nop 0
	global_load_dwordx2 v[14:15], v[24:25], off
	s_nop 0
	global_load_dwordx2 v[4:5], v[4:5], off
	s_nop 0
	global_load_dwordx2 v[8:9], v[22:23], off
	v_cmp_gt_i32_e64 s[8:9], 3, v19
	s_and_saveexec_b64 s[6:7], s[8:9]
	s_xor_b64 s[6:7], exec, s[6:7]
	v_mov_b64_e32 v[30:31], s[96:97]
	s_or_saveexec_b64 s[6:7], s[6:7]
	v_add_u32_e32 v22, s11, v19
	v_ashrrev_i32_e32 v23, 31, v22
	v_lshl_add_u64 v[28:29], v[22:23], 0, -3
	v_lshl_add_u64 v[26:27], v[22:23], 0, -2
	v_lshl_add_u64 v[24:25], v[22:23], 0, -1
	v_mov_b32_e32 v102, 0
	v_alignbit_b32 v55, v29, v28, 8
	v_lshlrev_b32_e32 v54, 9, v28
	v_alignbit_b32 v53, v27, v26, 8
	v_lshlrev_b32_e32 v28, 9, v26
	v_alignbit_b32 v26, v25, v24, 8
	v_lshlrev_b32_e32 v19, 9, v24
	v_mov_b32_e32 v104, 0
	v_mov_b32_e32 v105, 0
	s_xor_b64 exec, exec, s[6:7]
	s_cbranch_execz .LBB0_1311
	v_mad_u64_u32 v[48:49], s[14:15], v55, 49, s[96:97]
	v_mad_u32_u24 v49, v29, 49, v49
	v_lshlrev_b64 v[48:49], 17, v[48:49]
	v_lshl_add_u64 v[48:49], v[20:21], 0, v[48:49]
	v_and_b32_e32 v56, 0x1fe00, v54
	v_mov_b32_e32 v57, v167
	v_lshl_add_u64 v[48:49], v[48:49], 0, v[56:57]
	v_lshl_add_u64 v[48:49], v[48:49], 0, v[166:167]
	global_load_dword v102, v[48:49], off
	v_mad_u64_u32 v[48:49], s[14:15], v53, 49, s[96:97]
	v_mad_u32_u24 v49, v27, 49, v49
	v_lshlrev_b64 v[48:49], 17, v[48:49]
	v_lshl_add_u64 v[48:49], v[20:21], 0, v[48:49]
	v_and_b32_e32 v56, 0x1fe00, v28
	v_lshl_add_u64 v[48:49], v[48:49], 0, v[56:57]
	v_lshl_add_u64 v[48:49], v[48:49], 0, v[166:167]
	global_load_dword v104, v[48:49], off
	v_mad_u64_u32 v[48:49], s[14:15], v26, 49, s[96:97]
	v_mad_u32_u24 v49, v25, 49, v49
	v_lshlrev_b64 v[48:49], 17, v[48:49]
	v_lshl_add_u64 v[48:49], v[20:21], 0, v[48:49]
	v_and_b32_e32 v56, 0x1fe00, v19
	v_lshl_add_u64 v[48:49], v[48:49], 0, v[56:57]
	v_lshl_add_u64 v[48:49], v[48:49], 0, v[166:167]
	global_load_dword v105, v[48:49], off

.LBB0_1652:
	s_mov_b64 s[8:9], s[62:63]
	v_mov_b32_e32 v1, v208
	s_mov_b32 s2, 0x200000
	v_add_u32_e32 v90, s61, v1
	v_cmp_gt_i32_e32 vcc, s2, v90
	s_and_saveexec_b64 s[6:7], vcc
	v_readlane_b32 s83, v255, 3
	s_cbranch_execz .LBB0_1683
	v_mov_b32_e32 v0, 0
	s_load_dwordx2 s[10:11], s[8:9], 0xc0
	s_mov_b64 s[8:9], 0x2a4c2800
	v_readlane_b32 s0, v254, 36
	s_mov_b64 s[20:21], 0
	v_mov_b32_e32 v32, v0
	v_lshl_add_u32 v114, v1, 2, s0
	v_mov_b32_e32 v1, v0
	v_mov_b32_e32 v33, v0
	v_mov_b32_e32 v34, v0
	v_mov_b32_e32 v35, v0
	v_mov_b32_e32 v36, v0
	v_mov_b32_e32 v37, v0
	v_mov_b32_e32 v38, v0
	v_mov_b32_e32 v39, v0
	v_mov_b32_e32 v40, v0
	v_mov_b32_e32 v41, v0
	v_mov_b32_e32 v42, v0
	v_mov_b32_e32 v43, v0
	v_mov_b32_e32 v44, v0
	v_mov_b32_e32 v45, v0
	v_mov_b32_e32 v46, v0
	v_mov_b32_e32 v47, v0
	v_mov_b32_e32 v48, v0
	v_mov_b32_e32 v49, v0
	v_mov_b32_e32 v50, v0
	v_mov_b32_e32 v51, v0
	v_mov_b32_e32 v52, v0
	v_mov_b32_e32 v53, v0
	v_mov_b32_e32 v54, v0
	v_mov_b32_e32 v55, v0
	s_waitcnt lgkmcnt(0)
	v_mov_b32_e32 v2, s10
	v_mov_b32_e32 v3, s11
	v_lshl_add_u64 v[64:65], v[2:3], 0, s[8:9]
	s_mov_b64 s[8:9], 0x7442800
	v_lshl_add_u64 v[66:67], v[2:3], 0, s[8:9]
	s_mov_b64 s[8:9], 0x74c2800
	v_lshl_add_u64 v[68:69], v[2:3], 0, s[8:9]
	s_mov_b64 s[8:9], 0x20cc2800
	v_lshl_add_u64 v[70:71], v[2:3], 0, s[8:9]
	v_mov_b32_e32 v2, v0
	v_mov_b32_e32 v3, v0
	s_branch .LBB0_1655

.LBB0_1737:
	s_or_b64 exec, exec, s[6:7]
	s_mov_b64 s[6:7], s[62:63]
	s_waitcnt lgkmcnt(0)
	s_barrier
	s_load_dwordx2 s[14:15], s[6:7], 0xc0
	s_mov_b64 s[6:7], s[62:63]
	s_mov_b64 s[2:3], 0x244c2800
	s_mul_i32 s96, s83, 0x240000
	s_mov_b64 s[8:9], 0x3100000
	s_mov_b64 s[10:11], s[62:63]
	s_mov_b64 s[12:13], s[62:63]
	v_mov_b32_e32 v16, v208
	s_waitcnt lgkmcnt(0)
	v_mov_b32_e32 v0, s14
	v_mov_b32_e32 v1, s15
	v_lshl_add_u64 v[176:177], v[0:1], 0, s[2:3]
	s_load_dwordx2 s[14:15], s[6:7], 0xc0
	s_mov_b64 s[6:7], s[62:63]
	s_load_dwordx2 s[16:17], s[6:7], 0xc0
	s_mov_b64 s[2:3], 0x1fcc2800
	s_lshl_b64 s[6:7], s[96:97], 1
	s_waitcnt lgkmcnt(0)
	v_mov_b32_e32 v0, s14
	v_mov_b32_e32 v1, s15
	v_mov_b32_e32 v2, s16
	v_mov_b32_e32 v3, s17
	v_lshl_add_u64 v[0:1], v[0:1], 0, s[2:3]
	v_readlane_b32 s2, v253, 7
	v_readlane_b32 s3, v253, 8
	s_waitcnt vmcnt(0)
	v_lshl_add_u64 v[2:3], v[2:3], 0, s[6:7]
	v_lshl_add_u64 v[2:3], v[2:3], 0, s[8:9]
	v_readfirstlane_b32 s5, v1
	v_readfirstlane_b32 s28, v0
	v_readfirstlane_b32 s29, v16
	s_movk_i32 s8, 0x200
	v_readfirstlane_b32 s30, v3
	v_readfirstlane_b32 s31, v2
	s_and_b64 vcc, exec, s[2:3]
	s_cbranch_vccz .LBB0_1793
	v_lshlrev_b32_e32 v4, 4, v16
	v_add_u32_e32 v5, 0x2000, v4
	v_ashrrev_i32_e32 v6, 31, v5
	v_lshrrev_b32_e32 v6, 22, v6
	v_add_u32_e32 v6, v5, v6
	v_ashrrev_i32_e32 v6, 10, v6
	v_mul_i32_i24_e32 v7, 0x400, v6
	v_sub_u32_e32 v5, v5, v7
	v_lshrrev_b32_e32 v7, 4, v5
	v_bitop3_b32 v5, v7, v5, 32 bitop3:0x6c
	v_ashrrev_i32_e32 v7, 31, v5
	v_lshrrev_b32_e32 v7, 26, v7
	v_add_u32_e32 v7, v5, v7
	v_lshlrev_b32_e32 v9, 3, v6
	v_ashrrev_i32_e32 v8, 6, v7
	v_and_b32_e32 v9, -16, v9
	v_add_u32_e32 v9, v8, v9
	v_and_b32_e32 v8, 3, v8
	s_mov_b32 s0, 0x7fffffe0
	v_lshrrev_b32_e32 v10, 2, v9
	v_lshlrev_b32_e32 v11, 1, v9
	v_lshlrev_b32_e32 v6, 5, v6
	v_and_or_b32 v8, v9, s0, v8
	v_and_b32_e32 v10, 4, v10
	v_and_b32_e32 v11, 24, v11
	v_and_b32_e32 v17, 32, v6
	v_and_b32_e32 v6, 0xc0, v7
	v_or3_b32 v8, v8, v10, v11
	v_sub_u32_e32 v5, v5, v6
	v_mov_b32_e32 v11, 1
	v_ashrrev_i16_sdwa v5, v11, sext(v5) dst_sel:DWORD dst_unused:UNUSED_PAD src0_sel:DWORD src1_sel:BYTE_0
	v_bfe_i32 v18, v5, 0, 16
	v_mul_lo_u32 v8, v8, s8
	v_add_u32_e32 v5, v17, v18
	v_mul_lo_u32 v19, v9, s8
	v_add_lshl_u32 v178, v8, v5, 1
	v_add_lshl_u32 v180, v5, v19, 1
	v_bfe_i32 v5, v16, 27, 1
	v_lshrrev_b32_e32 v5, 22, v5
	v_add_u32_e32 v5, v4, v5
	v_and_b32_e32 v5, 0xfffffc00, v5
	v_sub_u32_e32 v4, v4, v5
	v_ashrrev_i32_e32 v6, 31, v16
	v_lshrrev_b32_e32 v5, 4, v4
	v_lshrrev_b32_e32 v6, 26, v6
	v_bitop3_b32 v5, v5, v4, 32 bitop3:0x6c
	v_ashrrev_i32_e32 v4, 31, v4
	v_add_u32_e32 v6, v16, v6
	v_lshrrev_b32_e32 v4, 26, v4
	v_ashrrev_i32_e32 v6, 6, v6
	v_add_u32_e32 v4, v5, v4
	v_lshlrev_b32_e32 v7, 3, v6
	v_ashrrev_i32_e32 v4, 6, v4
	v_and_b32_e32 v7, -16, v7
	s_ashr_i32 s9, s8, 31
	v_add_u32_e32 v7, v4, v7
	v_and_b32_e32 v8, 3, v4
	global_load_dwordx2 v[0:1], v167, s[10:11] offset:192
	global_load_dwordx2 v[2:3], v167, s[12:13] offset:192
	s_lshl_b64 s[12:13], s[8:9], 9
	v_and_or_b32 v8, v7, s0, v8
	v_readlane_b32 s0, v253, 46
	v_readlane_b32 s2, v253, 47
	s_mul_i32 s16, s12, s0
	s_mul_hi_u32 s17, s12, s70
	v_readlane_b32 s3, v253, 48
	v_mul_i32_i24_e32 v4, 64, v4
	s_add_i32 s18, s17, s16
	s_lshr_b64 s[16:17], s[8:9], 23
	s_mul_i32 s19, s12, s3
	s_mul_hi_u32 s20, s12, s2
	s_ashr_i32 s14, s29, 6
	v_lshrrev_b32_e32 v9, 2, v7
	v_lshlrev_b32_e32 v10, 1, v7
	v_sub_u32_e32 v4, v5, v4
	s_mul_i32 s17, s16, s70
	s_add_i32 s19, s20, s19
	s_mul_i32 s16, s16, s2
	s_ashr_i32 s15, s29, 8
	s_lshl_b64 s[10:11], s[8:9], 8
	s_lshl_b32 s34, s14, 10
	v_and_b32_e32 v9, 4, v9
	v_and_b32_e32 v10, 24, v10
	v_lshlrev_b32_e32 v6, 5, v6
	v_ashrrev_i16_sdwa v4, v11, sext(v4) dst_sel:DWORD dst_unused:UNUSED_PAD src0_sel:DWORD src1_sel:BYTE_0
	s_add_i32 s18, s18, s17
	s_add_i32 s19, s19, s16
	s_mul_i32 s16, s12, s2
	v_or3_b32 v8, v8, v9, v10
	v_and_b32_e32 v20, 32, v6
	v_bfe_i32 v21, v4, 0, 16
	s_add_u32 s24, s31, s16
	v_mul_lo_u32 v8, v8, s8
	v_add_u32_e32 v4, v20, v21
	s_addc_u32 s25, s30, s19
	s_add_i32 s35, s34, 0
	v_add_lshl_u32 v182, v8, v4, 1
	s_add_i32 m0, s35, 0x10000
	s_mul_i32 s17, s12, s70
	global_load_lds_dwordx4 v182, s[24:25]
	s_add_i32 m0, s35, 0x12000
	v_mul_lo_u32 v22, v7, s8
	s_add_u32 s26, s28, s17
	v_add_lshl_u32 v184, v4, v22, 1
	global_load_lds_dwordx4 v178, s[24:25]
	s_addc_u32 s27, s5, s18
	s_mov_b32 m0, s35
	s_add_i32 s36, s35, 0x2000
	global_load_lds_dwordx4 v184, s[26:27]
	s_mov_b32 m0, s36
	s_add_u32 s16, s24, s10
	global_load_lds_dwordx4 v180, s[26:27]
	s_addc_u32 s17, s25, s11
	s_add_i32 m0, s35, 0x14000
	v_mov_b32_e32 v183, v167
	v_mov_b32_e32 v179, v167
	global_load_lds_dwordx4 v182, s[16:17]
	s_add_i32 m0, s35, 0x16000
	v_lshl_add_u64 v[12:13], s[16:17], 0, v[182:183]
	v_lshl_add_u64 v[14:15], s[16:17], 0, v[178:179]
	global_load_lds_dwordx4 v178, s[16:17]
	s_add_u32 s16, s26, s10
	s_addc_u32 s17, s27, s11
	s_add_i32 s37, s35, 0x4000
	s_mov_b32 m0, s37
	s_add_i32 s38, s35, 0x6000
	global_load_lds_dwordx4 v184, s[16:17]
	s_mov_b32 m0, s38
	v_mov_b32_e32 v185, v167
	global_load_lds_dwordx4 v180, s[16:17]
	v_mov_b32_e32 v181, v167
	v_lshl_add_u64 v[4:5], s[24:25], 0, v[182:183]
	v_lshl_add_u64 v[6:7], s[24:25], 0, v[178:179]
	v_lshl_add_u64 v[8:9], s[26:27], 0, v[184:185]
	v_lshl_add_u64 v[10:11], s[26:27], 0, v[180:181]
	s_cmp_lg_u32 s15, 1
	s_cbranch_scc1 .LBB0_1740
	s_barrier

.LBB0_1793:
	s_mov_b64 s[8:9], s[62:63]
	s_load_dwordx2 s[12:13], s[8:9], 0xc0
	s_mov_b64 s[8:9], s[62:63]
	s_load_dwordx2 s[14:15], s[8:9], 0xc0
	s_mov_b64 s[2:3], 0x23cc2800
	s_mov_b64 s[10:11], s[62:63]
	v_mov_b32_e32 v148, v208
	s_movk_i32 s8, 0x100
	s_waitcnt lgkmcnt(0)
	v_mov_b32_e32 v132, s12
	v_mov_b32_e32 v133, s13
	v_mov_b32_e32 v134, s14
	v_mov_b32_e32 v135, s15
	v_lshl_add_u64 v[132:133], v[132:133], 0, s[2:3]
	v_readlane_b32 s2, v255, 1
	v_readlane_b32 s3, v255, 2
	v_lshl_add_u64 v[134:135], v[134:135], 0, s[6:7]
	s_mov_b64 s[6:7], 0x3500000
	v_lshl_add_u64 v[134:135], v[134:135], 0, s[6:7]
	s_mov_b64 s[6:7], s[62:63]
	v_readfirstlane_b32 s5, v133
	v_readfirstlane_b32 s24, v132
	v_readfirstlane_b32 s26, v135
	v_readfirstlane_b32 s25, v148
	v_readfirstlane_b32 s27, v134
	s_and_b64 vcc, exec, s[2:3]
	s_cbranch_vccnz .LBB0_1815
	v_lshlrev_b32_e32 v136, 4, v148
	v_add_u32_e32 v137, 0x2000, v136
	v_ashrrev_i32_e32 v138, 31, v137
	v_lshrrev_b32_e32 v138, 22, v138
	v_add_u32_e32 v138, v137, v138
	v_ashrrev_i32_e32 v138, 10, v138
	v_mul_i32_i24_e32 v139, 0x400, v138
	v_sub_u32_e32 v137, v137, v139
	v_lshrrev_b32_e32 v139, 4, v137
	v_bitop3_b32 v137, v139, v137, 32 bitop3:0x6c
	v_ashrrev_i32_e32 v139, 31, v137
	v_lshrrev_b32_e32 v139, 26, v139
	v_add_u32_e32 v139, v137, v139
	v_lshlrev_b32_e32 v141, 3, v138
	v_ashrrev_i32_e32 v140, 6, v139
	v_and_b32_e32 v141, -16, v141
	v_add_u32_e32 v141, v140, v141
	v_and_b32_e32 v140, 3, v140
	s_mov_b32 s0, 0x7fffffe0
	v_lshrrev_b32_e32 v142, 2, v141
	v_lshlrev_b32_e32 v143, 1, v141
	v_lshlrev_b32_e32 v138, 5, v138
	v_and_or_b32 v140, v141, s0, v140
	v_and_b32_e32 v142, 4, v142
	v_and_b32_e32 v143, 24, v143
	v_and_b32_e32 v149, 32, v138
	v_and_b32_e32 v138, 0xc0, v139
	v_or3_b32 v140, v140, v142, v143
	v_sub_u32_e32 v137, v137, v138
	v_mov_b32_e32 v143, 1
	v_ashrrev_i16_sdwa v137, v143, sext(v137) dst_sel:DWORD dst_unused:UNUSED_PAD src0_sel:DWORD src1_sel:BYTE_0
	v_bfe_i32 v150, v137, 0, 16
	v_mul_lo_u32 v140, v140, s8
	v_add_u32_e32 v137, v149, v150
	v_mul_lo_u32 v151, v141, s8
	v_add_lshl_u32 v156, v140, v137, 1
	v_add_lshl_u32 v158, v137, v151, 1
	v_bfe_i32 v137, v148, 27, 1
	v_lshrrev_b32_e32 v137, 22, v137
	v_add_u32_e32 v137, v136, v137
	v_and_b32_e32 v137, 0xfffffc00, v137
	v_sub_u32_e32 v136, v136, v137
	v_ashrrev_i32_e32 v138, 31, v148
	v_lshrrev_b32_e32 v137, 4, v136
	v_lshrrev_b32_e32 v138, 26, v138
	v_bitop3_b32 v137, v137, v136, 32 bitop3:0x6c
	v_ashrrev_i32_e32 v136, 31, v136
	v_add_u32_e32 v138, v148, v138
	v_lshrrev_b32_e32 v136, 26, v136
	v_ashrrev_i32_e32 v138, 6, v138
	v_add_u32_e32 v136, v137, v136
	v_lshlrev_b32_e32 v139, 3, v138
	v_ashrrev_i32_e32 v136, 6, v136
	v_and_b32_e32 v139, -16, v139
	s_ashr_i32 s9, s8, 31
	v_add_u32_e32 v139, v136, v139
	v_and_b32_e32 v140, 3, v136
	s_lshl_b64 s[14:15], s[8:9], 9
	v_and_or_b32 v140, v139, s0, v140
	v_readlane_b32 s0, v253, 46
	v_readlane_b32 s2, v253, 47
	s_mul_i32 s12, s14, s0
	s_mul_hi_u32 s13, s14, s70
	v_readlane_b32 s3, v253, 48
	v_mul_i32_i24_e32 v136, 64, v136
	s_add_i32 s16, s13, s12
	s_lshr_b64 s[12:13], s[8:9], 23
	s_mul_i32 s17, s14, s3
	s_mul_hi_u32 s18, s14, s2
	global_load_dwordx2 v[132:133], v167, s[6:7] offset:192
	global_load_dwordx2 v[134:135], v167, s[10:11] offset:192
	s_ashr_i32 s10, s25, 6
	v_lshrrev_b32_e32 v141, 2, v139
	v_lshlrev_b32_e32 v142, 1, v139
	v_sub_u32_e32 v136, v137, v136
	s_mul_i32 s13, s12, s70
	s_add_i32 s17, s18, s17
	s_mul_i32 s12, s12, s2
	s_ashr_i32 s11, s25, 8
	s_lshl_b64 s[6:7], s[8:9], 8
	s_lshl_b32 s28, s10, 10
	v_and_b32_e32 v141, 4, v141
	v_and_b32_e32 v142, 24, v142
	v_lshlrev_b32_e32 v138, 5, v138
	v_ashrrev_i16_sdwa v136, v143, sext(v136) dst_sel:DWORD dst_unused:UNUSED_PAD src0_sel:DWORD src1_sel:BYTE_0
	s_add_i32 s16, s16, s13
	s_add_i32 s17, s17, s12
	s_mul_i32 s12, s14, s2
	v_or3_b32 v140, v140, v141, v142
	v_and_b32_e32 v152, 32, v138
	v_bfe_i32 v153, v136, 0, 16
	s_add_u32 s18, s27, s12
	v_mul_lo_u32 v140, v140, s8
	v_add_u32_e32 v136, v152, v153
	s_addc_u32 s19, s26, s17
	s_add_i32 s29, s28, 0
	v_add_lshl_u32 v160, v140, v136, 1
	s_add_i32 m0, s29, 0x10000
	s_mul_i32 s13, s14, s70
	global_load_lds_dwordx4 v160, s[18:19]
	s_add_i32 m0, s29, 0x12000
	v_mul_lo_u32 v154, v139, s8
	s_add_u32 s20, s24, s13
	v_add_lshl_u32 v162, v136, v154, 1
	global_load_lds_dwordx4 v156, s[18:19]
	s_addc_u32 s21, s5, s16
	s_mov_b32 m0, s29
	s_add_i32 s30, s29, 0x2000
	global_load_lds_dwordx4 v162, s[20:21]
	s_mov_b32 m0, s30
	s_add_u32 s12, s18, s6
	global_load_lds_dwordx4 v158, s[20:21]
	s_addc_u32 s13, s19, s7
	s_add_i32 m0, s29, 0x14000
	v_mov_b32_e32 v161, v167
	v_mov_b32_e32 v157, v167
	global_load_lds_dwordx4 v160, s[12:13]
	s_add_i32 m0, s29, 0x16000
	v_lshl_add_u64 v[144:145], s[12:13], 0, v[160:161]
	v_lshl_add_u64 v[146:147], s[12:13], 0, v[156:157]
	global_load_lds_dwordx4 v156, s[12:13]
	s_add_u32 s12, s20, s6
	s_addc_u32 s13, s21, s7
	s_add_i32 s31, s29, 0x4000
	s_mov_b32 m0, s31
	s_add_i32 s34, s29, 0x6000
	global_load_lds_dwordx4 v162, s[12:13]
	s_mov_b32 m0, s34
	v_mov_b32_e32 v163, v167
	global_load_lds_dwordx4 v158, s[12:13]
	v_mov_b32_e32 v159, v167
	v_readlane_b32 s2, v253, 3
	v_lshl_add_u64 v[136:137], s[18:19], 0, v[160:161]
	v_lshl_add_u64 v[138:139], s[18:19], 0, v[156:157]
	v_lshl_add_u64 v[140:141], s[20:21], 0, v[162:163]
	v_lshl_add_u64 v[142:143], s[20:21], 0, v[158:159]
	s_cmp_lg_u32 s11, 1
	v_readlane_b32 s3, v253, 4
	s_cbranch_scc1 .LBB0_1796
	s_barrier

.LBB0_1869:
	s_or_b64 exec, exec, s[6:7]
	s_mov_b64 s[6:7], s[62:63]
	s_waitcnt lgkmcnt(0)
	s_barrier
	s_load_dwordx2 s[12:13], s[6:7], 0xc0
	s_mov_b64 s[6:7], s[62:63]
	s_load_dwordx2 s[14:15], s[6:7], 0xc0
	v_readlane_b32 s2, v255, 1
	v_readlane_b32 s3, v255, 2
	s_lshl_b32 s96, s83, 21
	s_and_b64 vcc, exec, s[2:3]
	s_mov_b64 s[2:3], 0x5300000
	s_mov_b64 s[10:11], 0x4300000
	s_mov_b64 s[8:9], s[62:63]
	v_mov_b32_e32 v0, v208
	s_movk_i32 s6, 0x400
	s_waitcnt lgkmcnt(0)
	v_mov_b32_e32 v2, s12
	v_mov_b32_e32 v3, s13
	v_mov_b32_e32 v4, s14
	v_mov_b32_e32 v5, s15
	v_lshl_add_u64 v[2:3], v[2:3], 0, s[2:3]
	s_nop 0
	v_readfirstlane_b32 s24, v3
	v_readfirstlane_b32 s25, v2
	s_waitcnt vmcnt(0)
	v_lshl_add_u64 v[4:5], v[4:5], 0, s[96:97]
	v_lshl_add_u64 v[2:3], v[4:5], 0, s[10:11]
	v_readfirstlane_b32 s5, v0
	v_readfirstlane_b32 s26, v3
	v_readfirstlane_b32 s27, v2
	s_cbranch_vccnz .LBB0_1891
	v_lshlrev_b32_e32 v1, 4, v0
	v_add_u32_e32 v2, 0x2000, v1
	v_ashrrev_i32_e32 v3, 31, v2
	v_lshrrev_b32_e32 v3, 22, v3
	v_add_u32_e32 v3, v2, v3
	v_ashrrev_i32_e32 v3, 10, v3
	v_mul_i32_i24_e32 v4, 0x400, v3
	v_sub_u32_e32 v2, v2, v4
	v_lshrrev_b32_e32 v4, 4, v2
	v_bitop3_b32 v4, v4, v2, 32 bitop3:0x6c
	v_ashrrev_i32_e32 v2, 31, v4
	v_lshrrev_b32_e32 v2, 26, v2
	v_add_u32_e32 v5, v4, v2
	v_lshlrev_b32_e32 v6, 3, v3
	v_ashrrev_i32_e32 v2, 6, v5
	v_and_b32_e32 v6, 0x7ffffff0, v6
	v_add_u32_e32 v6, v2, v6
	v_lshlrev_b32_e32 v2, 5, v3
	v_and_b32_e32 v2, 32, v2
	global_load_dwordx2 v[132:133], v167, s[8:9] offset:184
	v_mad_u64_u32 v[2:3], s[8:9], v6, s6, v[2:3]
	v_and_b32_e32 v3, 0xc0, v5
	v_sub_u32_e32 v3, v4, v3
	v_mov_b32_e32 v5, 1
	v_ashrrev_i16_sdwa v3, v5, sext(v3) dst_sel:DWORD dst_unused:UNUSED_PAD src0_sel:DWORD src1_sel:BYTE_0
	v_bfe_i32 v3, v3, 0, 16
	v_add_lshl_u32 v134, v2, v3, 1
	v_bfe_i32 v2, v0, 27, 1
	v_lshrrev_b32_e32 v2, 22, v2
	v_add_u32_e32 v2, v1, v2
	v_and_b32_e32 v2, 0xfffffc00, v2
	v_sub_u32_e32 v1, v1, v2
	v_lshrrev_b32_e32 v2, 4, v1
	v_bitop3_b32 v4, v2, v1, 32 bitop3:0x6c
	v_ashrrev_i32_e32 v2, 31, v0
	v_lshrrev_b32_e32 v2, 26, v2
	v_ashrrev_i32_e32 v1, 31, v1
	v_add_u32_e32 v2, v0, v2
	v_lshrrev_b32_e32 v1, 26, v1
	v_ashrrev_i32_e32 v2, 6, v2
	v_add_u32_e32 v1, v4, v1
	v_lshlrev_b32_e32 v3, 3, v2
	v_ashrrev_i32_e32 v1, 6, v1
	v_and_b32_e32 v3, 0x7ffffff0, v3
	v_lshlrev_b32_e32 v2, 5, v2
	s_ashr_i32 s7, s6, 31
	v_add_u32_e32 v3, v1, v3
	v_and_b32_e32 v2, 32, v2
	s_lshl_b64 s[14:15], s[6:7], 9
	v_mad_u64_u32 v[2:3], s[8:9], v3, s6, v[2:3]
	v_readlane_b32 s0, v253, 46
	v_readlane_b32 s2, v253, 47
	s_mul_i32 s8, s14, s0
	s_mul_hi_u32 s9, s14, s70
	v_readlane_b32 s3, v253, 48
	s_add_i32 s16, s9, s8
	s_lshr_b64 s[8:9], s[6:7], 23
	s_mul_i32 s17, s14, s3
	s_mul_hi_u32 s18, s14, s2
	s_ashr_i32 s10, s5, 6
	v_mul_i32_i24_e32 v1, 64, v1
	s_mul_i32 s9, s8, s70
	s_add_i32 s17, s18, s17
	s_mul_i32 s8, s8, s2
	s_ashr_i32 s11, s5, 8
	s_lshl_b64 s[12:13], s[6:7], 8
	s_lshl_b32 s28, s10, 10
	v_sub_u32_e32 v1, v4, v1
	s_add_i32 s16, s16, s9
	s_add_i32 s17, s17, s8
	s_mul_i32 s8, s14, s2
	v_ashrrev_i16_sdwa v1, v5, sext(v1) dst_sel:DWORD dst_unused:UNUSED_PAD src0_sel:DWORD src1_sel:BYTE_0
	s_add_u32 s18, s27, s8
	v_bfe_i32 v1, v1, 0, 16
	s_addc_u32 s19, s26, s17
	s_add_i32 s29, s28, 0
	v_add_lshl_u32 v166, v2, v1, 1
	s_add_i32 m0, s29, 0x10000
	s_mul_i32 s9, s14, s70
	global_load_lds_dwordx4 v166, s[18:19]
	s_add_i32 m0, s29, 0x12000
	s_add_u32 s20, s25, s9
	global_load_lds_dwordx4 v134, s[18:19]
	s_addc_u32 s21, s24, s16
	s_mov_b32 m0, s29
	s_add_i32 s30, s29, 0x2000
	global_load_lds_dwordx4 v166, s[20:21]
	s_mov_b32 m0, s30
	s_add_u32 s8, s18, s12
	global_load_lds_dwordx4 v134, s[20:21]
	s_addc_u32 s9, s19, s13
	s_add_i32 m0, s29, 0x14000
	v_readlane_b32 s2, v253, 3
	global_load_lds_dwordx4 v166, s[8:9]
	s_add_i32 m0, s29, 0x16000
	s_add_u32 s16, s20, s12
	s_addc_u32 s17, s21, s13
	s_add_i32 s31, s29, 0x4000
	global_load_lds_dwordx4 v134, s[8:9]
	s_mov_b32 m0, s31
	s_add_i32 s34, s29, 0x6000
	global_load_lds_dwordx4 v166, s[16:17]
	s_mov_b32 m0, s34
	s_cmp_lg_u32 s11, 1
	global_load_lds_dwordx4 v134, s[16:17]
	v_readlane_b32 s3, v253, 4
	s_cbranch_scc1 .LBB0_1872
	s_barrier
